# adds: state-update LDS addresses of waves 4-7 hoisted, wave-3-only prelude moved, dead register copies of waves 0-2 removed
# speedup vs baseline: 1.0007x; 1.0007x over previous
.LBB0_706:
	s_or_b64 exec, exec, s[46:47]
	s_lshl_b64 s[44:45], s[44:45], 11
	s_lshl_b64 s[34:35], s[34:35], 1
	s_add_u32 s34, s50, s34
	s_addc_u32 s35, s90, s35
	s_lshl_b32 s41, s41, 5
	s_and_b32 s41, s41, 0x300
	s_waitcnt vmcnt(7)
	v_mul_f32_e32 v2, 0x3fb8aa3b, v4
	s_add_u32 s46, s34, s41
	v_lshlrev_b32_e32 v6, 6, v151
	s_mov_b32 s34, 0x8000
	v_exp_f32_e32 v163, v2
	v_and_b32_e32 v2, 0xfc00, v6
	v_bitop3_b32 v6, v6, s34, v145 bitop3:0x6c
	s_addc_u32 s47, s35, 0
	v_lshlrev_b32_e32 v2, 1, v2
	v_mov_b32_e32 v3, v50
	v_lshlrev_b32_e32 v4, 4, v151
	v_lshlrev_b32_e32 v6, 1, v6
	v_mov_b32_e32 v7, v50
	v_lshl_add_u64 v[2:3], s[46:47], 0, v[2:3]
	v_and_b32_e32 v4, 0xf0, v4
	v_mov_b32_e32 v5, v50
	v_lshl_add_u64 v[6:7], s[46:47], 0, v[6:7]
	v_and_b32_e32 v162, 63, v151
	v_lshl_add_u64 v[2:3], v[2:3], 0, v[4:5]
	v_lshl_add_u64 v[4:5], v[6:7], 0, v[4:5]
	v_ashrrev_i32_e32 v141, 31, v140
	global_load_dwordx4 v[102:105], v[2:3], off
	global_load_dwordx4 v[106:109], v[2:3], off offset:1024
	global_load_dwordx4 v[110:113], v[4:5], off
	global_load_dwordx4 v[114:117], v[4:5], off offset:1024
	v_or_b32_e32 v2, s44, v162
	v_mov_b32_e32 v3, s45
	v_lshl_add_u64 v[4:5], s[44:45], 0, v[140:141]
	v_lshlrev_b64 v[2:3], 7, v[2:3]
	v_lshlrev_b64 v[4:5], 11, v[4:5]
	s_and_b32 s34, s39, 0x3c0
	v_lshl_add_u64 v[2:3], s[20:21], 0, v[2:3]
	v_lshl_add_u64 v[4:5], s[52:53], 0, v[4:5]
	s_lshl_b32 s34, s34, 1
	s_mov_b32 s35, s11
	v_and_b32_e32 v165, 7, v151
	v_lshl_add_u64 v[2:3], v[2:3], 0, s[10:11]
	v_lshl_add_u64 v[4:5], v[4:5], 0, s[34:35]
	v_lshlrev_b32_e32 v6, 4, v165
	v_mov_b32_e32 v7, v50
	s_waitcnt lgkmcnt(0)
	s_barrier
	v_lshl_add_u64 v[4:5], v[4:5], 0, v[6:7]
	global_load_dword v18, v[2:3], off
	global_load_dwordx4 v[118:121], v[4:5], off nt
	s_add_u32 s48, s20, s10
	s_addc_u32 s49, s21, 0
	s_add_u32 s52, s52, s34
	s_addc_u32 s53, s53, 0
	s_add_u32 s54, s4, s10
	s_addc_u32 s55, s5, 0
	s_or_b32 s41, s44, 64
	s_lshl_b32 s34, s39, 1
	s_add_u32 s56, s0, s34
	v_lshlrev_b32_e32 v144, 3, v165
	s_mov_b32 s43, s45
	s_addc_u32 s57, s1, 0
	s_mov_b32 s66, 0
	s_mov_b64 s[70:71], 0
	s_mov_b32 s82, 0
	v_mov_b32_e32 v2, 0
	v_mov_b32_e32 v3, v166
	v_mov_b32_e32 v4, v166
	v_mov_b32_e32 v5, v166
	v_mov_b32_e32 v6, v166
	v_mov_b32_e32 v7, v166
	v_mov_b32_e32 v8, v166
	v_mov_b32_e32 v9, v166
	v_mov_b32_e32 v10, v166
	v_mov_b32_e32 v11, v166
	v_mov_b32_e32 v12, v166
	v_mov_b32_e32 v13, v166
	v_mov_b32_e32 v14, v166
	v_mov_b32_e32 v15, v166
	v_mov_b32_e32 v16, v166
	v_mov_b32_e32 v17, v166
	v_mov_b32_e32 v98, 0
	v_mov_b32_e32 v99, v166
	v_mov_b32_e32 v100, v166
	v_mov_b32_e32 v101, v166
	v_mov_b32_e32 v94, v166
	v_mov_b32_e32 v95, v166
	v_mov_b32_e32 v96, v166
	v_mov_b32_e32 v97, v166
	v_mov_b32_e32 v90, v166
	v_mov_b32_e32 v91, v166
	v_mov_b32_e32 v92, v166
	v_mov_b32_e32 v93, v166
	v_mov_b32_e32 v86, v166
	v_mov_b32_e32 v87, v166
	v_mov_b32_e32 v88, v166
	v_mov_b32_e32 v89, v166
	v_mov_b32_e32 v82, 0
	v_mov_b32_e32 v83, v166
	v_mov_b32_e32 v84, v166
	v_mov_b32_e32 v85, v166
	v_mov_b32_e32 v78, v166
	v_mov_b32_e32 v79, v166
	v_mov_b32_e32 v80, v166
	v_mov_b32_e32 v81, v166
	v_mov_b32_e32 v74, v166
	v_mov_b32_e32 v75, v166
	v_mov_b32_e32 v76, v166
	v_mov_b32_e32 v77, v166
	v_mov_b32_e32 v70, v166
	v_mov_b32_e32 v71, v166
	v_mov_b32_e32 v72, v166
	v_mov_b32_e32 v73, v166
	v_mov_b32_e32 v66, 0
	v_mov_b32_e32 v67, v166
	v_mov_b32_e32 v68, v166
	v_mov_b32_e32 v69, v166
	v_mov_b32_e32 v62, v166
	v_mov_b32_e32 v63, v166
	v_mov_b32_e32 v64, v166
	v_mov_b32_e32 v65, v166
	v_mov_b32_e32 v58, v166
	v_mov_b32_e32 v59, v166
	v_mov_b32_e32 v60, v166
	v_mov_b32_e32 v61, v166
	v_mov_b32_e32 v54, v166
	v_mov_b32_e32 v55, v166
	v_mov_b32_e32 v56, v166
	v_mov_b32_e32 v57, v166
	v_mov_b32_e32 v126, 0
	v_mov_b32_e32 v127, v166
	v_mov_b32_e32 v128, v166
	v_mov_b32_e32 v129, v166
	v_mov_b32_e32 v167, v151
	v_ashrrev_i32_e32 v146, 3, v151
	s_mov_b32 s98, 0x20000
	s_mov_b32 s99, 0
	v_lshlrev_b32_e32 v212, 4, v151
	v_lshrrev_b32_e32 v213, 2, v151
	v_and_b32_e32 v214, 15, v151
	v_bfe_u32 v215, v151, 6, 2
	v_and_b32_e32 v213, 12, v213
	v_bitop3_b32 v213, v213, v214, v215 bitop3:0x36
	v_and_b32_e32 v216, 0x3f00, v212
	v_lshlrev_b32_e32 v213, 4, v213
	v_add3_u32 v196, 0, v216, v213
	v_add_u32_e32 v217, 0x200, v151
	v_lshrrev_b32_e32 v218, 2, v217
	v_and_b32_e32 v218, 12, v218
	v_lshlrev_b32_e32 v219, 4, v217
	v_bitop3_b32 v218, v218, v214, v215 bitop3:0x36
	v_and_b32_e32 v219, 0x3f00, v219
	v_lshlrev_b32_e32 v218, 4, v218
	v_add3_u32 v197, 0, v219, v218
	v_lshlrev_b32_e32 v213, 3, v151
	v_and_b32_e32 v213, 0x78, v213
	v_lshl_add_u32 v216, v213, 1, 0
	v_bfe_u32 v218, v151, 4, 6
	v_mad_u32_u24 v198, v218, s58, v216
	v_lshrrev_b32_e32 v219, 4, v151
	v_bitop3_b32 v219, v219, 32, 63 bitop3:0x6c
	v_mad_u32_u24 v199, v219, s58, v216
	v_or_b32_e32 v204, 64, v218
	v_lshlrev_b32_e32 v204, 11, v204
	v_mov_b32_e32 v205, 0
	v_mov_b32_e32 v217, 0
	v_lshl_add_u64 v[204:205], s[46:47], 0, v[204:205]
	v_or_b32_e32 v206, 64, v219
	v_lshl_add_u64 v[204:205], v[204:205], 0, v[216:217]
	v_lshlrev_b32_e32 v206, 11, v206
	v_mov_b32_e32 v207, 0
	v_and_b32_e32 v200, -4, v146
	v_lshl_add_u64 v[206:207], s[46:47], 0, v[206:207]
	v_add_u32_e32 v202, 0x43, v200
	v_lshl_add_u64 v[206:207], v[206:207], 0, v[216:217]
	v_add_u32_e32 v200, 63, v200
	v_lshlrev_b32_e32 v202, 11, v202
	v_lshlrev_b32_e32 v200, 11, v200
	v_mov_b32_e32 v201, 0
	v_mov_b32_e32 v203, 0
	v_lshl_add_u64 v[200:201], v[142:143], 0, v[200:201]
	v_lshl_add_u64 v[202:203], v[142:143], 0, v[202:203]
	s_mov_b32 s100, 0x2000
	s_mov_b32 s101, 0
	s_mov_b32 s68, s41
	s_mov_b32 s69, s43
	v_mov_b32_e32 v208, v162
	v_mov_b32_e32 v209, 0
	v_mov_b32_e32 v210, v146
	v_mov_b32_e32 v211, 0
	v_lshl_add_u64 v[208:209], s[68:69], 0, v[208:209]
	v_lshl_add_u64 v[210:211], s[68:69], 0, v[210:211]
	v_lshlrev_b64 v[208:209], 7, v[208:209]
	v_lshlrev_b64 v[210:211], 11, v[210:211]
	v_lshl_add_u64 v[208:209], s[48:49], 0, v[208:209]
	v_lshl_add_u64 v[210:211], s[52:53], 0, v[210:211]
	v_and_b32_e32 v220, 0x70, v212
	v_mov_b32_e32 v221, 0
	v_mov_b32_e32 v213, 0
	v_lshl_add_u64 v[210:211], v[210:211], 0, v[220:221]
	v_mov_b32_e32 v212, v146
	v_and_b32_e32 v220, 7, v151
	v_lshl_add_u64 v[212:213], s[44:45], 0, v[212:213]
	v_lshlrev_b32_e32 v222, 4, v220
	v_lshlrev_b64 v[214:215], 7, v[212:213]
	v_lshlrev_b64 v[212:213], 12, v[212:213]
	v_mov_b32_e32 v223, 0
	v_lshl_add_u64 v[214:215], s[54:55], 0, v[214:215]
	v_lshl_add_u64 v[212:213], s[56:57], 0, v[212:213]
	v_lshrrev_b32_e32 v221, 3, v151
	v_lshl_add_u64 v[212:213], v[212:213], 0, v[222:223]
	v_lshlrev_b32_e32 v222, 1, v220
	v_lshlrev_b32_e32 v223, 8, v146
	v_bitop3_b32 v221, v222, v221, 15 bitop3:0x78
	v_add_u32_e32 v224, s63, v223
	v_lshlrev_b32_e32 v225, 5, v220
	v_lshl_add_u32 v216, v221, 4, v224
	s_mov_b32 vcc_lo, 0x1bc00
	v_bfe_u32 v226, v151, 3, 4
	v_add3_u32 v217, vcc_lo, v223, v225
	v_bitop3_b32 v226, v222, v226, 1 bitop3:0x36
	v_xor_b32_e32 v227, v146, v151
	v_lshl_add_u32 v218, v226, 4, v224
	v_lshlrev_b32_e32 v227, 4, v227
	v_lshl_add_u32 v228, v146, 7, s64
	v_and_b32_e32 v227, 0x70, v227
	s_movk_i32 vcc_lo, 0xf000
	v_lshlrev_b32_e32 v231, 1, v151
	v_add3_u32 v219, v228, v227, vcc_lo
	v_and_b32_e32 v231, 62, v231
	v_and_b32_e32 v232, -4, v146
	v_mul_u32_u24_e32 v231, 0x48, v231
	v_lshlrev_b32_e32 v232, 1, v232
	v_lshlrev_b32_e32 v231, 1, v231
	s_nop 0
	v_add3_u32 v229, 0, v231, v232
	v_add3_u32 v230, s60, v231, v232
	v_add_u32_e32 v229, 0xd000, v229
	s_lshl_b32 vcc_lo, s33, 5
	v_lshl_add_u32 v241, v153, 4, vcc_lo
	v_add_u32_e32 v242, 4, v241
	v_add_u32_e32 v243, 8, v241
	v_add_u32_e32 v244, 12, v241
	v_mul_lo_u32 v245, v150, s58
	v_add_u32_e32 v247, s95, v150
	v_lshl_add_u32 v246, v153, 4, s92
	v_mul_lo_u32 v247, v247, s61
	v_lshlrev_b32_e32 v248, 2, v153
	v_lshl_add_u32 v245, v153, 4, v245
	v_lshlrev_b32_e32 v249, 3, v153
	v_add_lshl_u32 v248, v248, s89, 8
	v_lshlrev_b32_e32 v250, 2, v150
	v_add3_u32 v247, s94, v247, v249
	v_add3_u32 v248, s93, v250, v248
	v_lshrrev_b32_e32 v220, 3, v162
	v_lshlrev_b32_e32 v221, 1, v153
	v_lshlrev_b32_e32 v222, 3, v162
	v_and_b32_e32 v220, 2, v220
	v_bfe_u32 v223, v162, 2, 2
	v_bfe_u32 v224, v162, 1, 1
	v_and_b32_e32 v221, 2, v221
	v_and_b32_e32 v222, 8, v222
	v_lshlrev_b32_e32 v225, 3, v153
	v_or_b32_e32 v224, s25, v224
	v_lshl_or_b32 v226, v223, 2, v221
	v_or_b32_e32 v227, v224, v220
	v_or_b32_e32 v228, v223, v225
	v_bitop3_b32 v224, v224, v226, v220 bitop3:0x36
	v_lshl_add_u32 v228, v228, 8, 0
	v_lshlrev_b32_e32 v224, 4, v224
	v_bitop3_b32 v227, v226, v227, 1 bitop3:0x36
	v_add_u32_e32 v226, s95, v150
	v_lshlrev_b32_e32 v227, 4, v227
	v_mul_lo_u32 v220, v226, s61
	v_add3_u32 v251, v228, v224, v222
	v_add3_u32 v252, v228, v227, v222
	v_lshlrev_b32_e32 v221, 4, v153
	v_mul_lo_u32 v249, v226, s58
	v_add3_u32 v253, s60, v220, v221
	v_add_u32_e32 v249, v249, v225

.LBB0_731:
	s_andn2_b64 vcc, exec, s[12:13]
	s_cbranch_vccnz .LBB0_737
	s_nop 0
	v_mov_b32_e32 v18, s65
	ds_read_b32 v52, v18
	s_mov_b64 s[70:71], -1
	s_and_b64 vcc, exec, s[6:7]
	s_cbranch_vccz .LBB0_734
	ds_read_b64_tr_b16 v[18:19], v251
	ds_read_b64_tr_b16 v[20:21], v252 offset:1024
	ds_read_b128 v[22:25], v253
	ds_read_b128 v[34:37], v253 offset:32
	s_waitcnt lgkmcnt(1)
	v_mfma_f32_32x32x16_bf16 v[18:33], v[18:21], v[22:25], 0
	ds_read_b64_tr_b16 v[38:39], v251 offset:4096
	ds_read_b64_tr_b16 v[40:41], v252 offset:5120
	ds_read_b64_tr_b16 v[178:179], v251 offset:8192
	ds_read_b64_tr_b16 v[180:181], v252 offset:9216
	ds_read_b128 v[182:185], v253 offset:64
	s_xor_b32 s34, s66, 1
	s_mulk_i32 s34, 0x4400
	s_add_i32 s34, s34, 0
	s_add_i32 s34, s26, s34
	s_mov_b64 s[70:71], 0
	s_waitcnt lgkmcnt(3)
	v_mfma_f32_32x32x16_bf16 v[34:49], v[38:41], v[34:37], 0
	s_waitcnt lgkmcnt(0)
	v_mfma_f32_32x32x16_bf16 v[18:33], v[178:181], v[182:185], v[18:33]
	ds_read_b64_tr_b16 v[178:179], v251 offset:12288
	ds_read_b64_tr_b16 v[180:181], v252 offset:13312
	ds_read_b128 v[182:185], v253 offset:96
	s_waitcnt lgkmcnt(0)
	v_mfma_f32_32x32x16_bf16 v[34:49], v[178:181], v[182:185], v[34:49]
	s_nop 11
	v_pk_add_f32 v[20:21], v[20:21], v[36:37]
	v_pk_add_f32 v[18:19], v[18:19], v[34:35]
	v_pk_add_f32 v[32:33], v[32:33], v[48:49]
	v_pk_add_f32 v[30:31], v[30:31], v[46:47]
	v_pk_add_f32 v[28:29], v[28:29], v[44:45]
	v_pk_add_f32 v[26:27], v[26:27], v[42:43]
	v_pk_add_f32 v[24:25], v[24:25], v[40:41]
	v_pk_add_f32 v[22:23], v[22:23], v[38:39]
	v_pk_fma_f32 v[18:19], v[2:3], v[52:53], v[18:19] op_sel_hi:[1,0,1]
	v_pk_fma_f32 v[20:21], v[4:5], v[52:53], v[20:21] op_sel_hi:[1,0,1]
	v_pk_fma_f32 v[22:23], v[6:7], v[52:53], v[22:23] op_sel_hi:[1,0,1]
	v_pk_fma_f32 v[24:25], v[8:9], v[52:53], v[24:25] op_sel_hi:[1,0,1]
	v_pk_fma_f32 v[26:27], v[10:11], v[52:53], v[26:27] op_sel_hi:[1,0,1]
	v_pk_fma_f32 v[28:29], v[12:13], v[52:53], v[28:29] op_sel_hi:[1,0,1]
	v_pk_fma_f32 v[30:31], v[14:15], v[52:53], v[30:31] op_sel_hi:[1,0,1]
	v_pk_fma_f32 v[32:33], v[16:17], v[52:53], v[32:33] op_sel_hi:[1,0,1]
	v_add_u32_e32 v36, s34, v249
	v_cvt_pk_bf16_f32 v34, v18, v19
	v_cvt_pk_bf16_f32 v35, v20, v21
	v_add_u32_e32 v46, 0xf400, v36
	ds_write_b64 v36, v[34:35] offset:62464
	v_mov_b64_e32 v[34:35], v[32:33]
	v_mov_b64_e32 v[36:37], v[30:31]
	v_mov_b64_e32 v[38:39], v[28:29]
	v_mov_b64_e32 v[40:41], v[26:27]
	v_mov_b64_e32 v[42:43], v[24:25]
	v_mov_b64_e32 v[44:45], v[22:23]
.LBB0_734:
	s_andn2_b64 vcc, exec, s[70:71]
	s_cbranch_vccnz .LBB0_736
	v_lshrrev_b32_e32 v18, 3, v148
	v_and_b32_e32 v171, 2, v18
	v_lshlrev_b32_e32 v18, 1, v169
	v_lshlrev_b32_e32 v19, 3, v148
	v_bfe_u32 v170, v148, 2, 2
	v_bfe_u32 v172, v148, 1, 1
	v_and_b32_e32 v173, 2, v18
	v_and_b32_e32 v148, 8, v19
	v_lshlrev_b32_e32 v18, 11, v169
	v_lshlrev_b32_e32 v19, 8, v170
	v_or_b32_e32 v177, v171, v172
	v_add3_u32 v182, 0, v18, v19
	v_lshlrev_b32_e32 v18, 2, v170
	v_or_b32_e32 v183, v18, v173
	v_bitop3_b32 v18, v18, v177, v173 bitop3:0x36
	v_lshlrev_b32_e32 v18, 4, v18
	v_bitop3_b32 v19, v183, v177, 1 bitop3:0x36
	v_lshlrev_b32_e32 v19, 4, v19
	v_mul_lo_u32 v20, v168, s61
	v_add3_u32 v184, v182, v18, v148
	v_add3_u32 v185, v182, v19, v148
	v_add3_u32 v147, s60, v20, v147
	ds_read_b64_tr_b16 v[18:19], v184
	ds_read_b64_tr_b16 v[20:21], v185 offset:1024
	ds_read_b128 v[22:25], v147
	ds_read_b128 v[34:37], v147 offset:32
	s_waitcnt lgkmcnt(1)
	v_mfma_f32_32x32x16_bf16 v[18:33], v[18:21], v[22:25], 0
	ds_read_b64_tr_b16 v[38:39], v184 offset:4096
	ds_read_b64_tr_b16 v[40:41], v185 offset:5120
	ds_read_b64_tr_b16 v[170:171], v184 offset:8192
	ds_read_b64_tr_b16 v[172:173], v185 offset:9216
	ds_read_b128 v[178:181], v147 offset:64
	s_xor_b32 s34, s66, 1
	s_mulk_i32 s34, 0x4400
	s_add_i32 s34, s34, 0
	s_waitcnt lgkmcnt(3)
	v_mfma_f32_32x32x16_bf16 v[34:49], v[38:41], v[34:37], 0
	s_waitcnt lgkmcnt(0)
	v_mfma_f32_32x32x16_bf16 v[18:33], v[170:173], v[178:181], v[18:33]
	ds_read_b64_tr_b16 v[170:171], v184 offset:12288
	ds_read_b64_tr_b16 v[172:173], v185 offset:13312
	ds_read_b128 v[178:181], v147 offset:96
	s_waitcnt lgkmcnt(0)
	v_mfma_f32_32x32x16_bf16 v[34:49], v[170:173], v[178:181], v[34:49]
	s_nop 11
	v_pk_add_f32 v[18:19], v[18:19], v[34:35]
	v_pk_add_f32 v[32:33], v[32:33], v[48:49]
	v_pk_add_f32 v[30:31], v[30:31], v[46:47]
	v_pk_add_f32 v[28:29], v[28:29], v[44:45]
	v_pk_add_f32 v[26:27], v[26:27], v[42:43]
	v_pk_add_f32 v[24:25], v[24:25], v[40:41]
	v_pk_add_f32 v[22:23], v[22:23], v[38:39]
	v_pk_add_f32 v[20:21], v[20:21], v[36:37]
	v_pk_fma_f32 v[18:19], v[2:3], v[52:53], v[18:19] op_sel_hi:[1,0,1]
	v_mul_lo_u32 v2, v168, s58
	v_pk_fma_f32 v[20:21], v[4:5], v[52:53], v[20:21] op_sel_hi:[1,0,1]
	v_pk_fma_f32 v[22:23], v[6:7], v[52:53], v[22:23] op_sel_hi:[1,0,1]
	v_pk_fma_f32 v[24:25], v[8:9], v[52:53], v[24:25] op_sel_hi:[1,0,1]
	v_pk_fma_f32 v[26:27], v[10:11], v[52:53], v[26:27] op_sel_hi:[1,0,1]
	v_pk_fma_f32 v[28:29], v[12:13], v[52:53], v[28:29] op_sel_hi:[1,0,1]
	v_pk_fma_f32 v[30:31], v[14:15], v[52:53], v[30:31] op_sel_hi:[1,0,1]
	v_pk_fma_f32 v[32:33], v[16:17], v[52:53], v[32:33] op_sel_hi:[1,0,1]
	v_add3_u32 v53, s34, v2, v53
	v_cvt_pk_bf16_f32 v2, v18, v19
	v_cvt_pk_bf16_f32 v3, v20, v21
	v_cvt_pk_bf16_f32 v4, v22, v23
	v_cvt_pk_bf16_f32 v5, v24, v25
	v_add_u32_e32 v172, 0xf000, v53
	ds_write2_b64 v172, v[2:3], v[4:5] offset0:128 offset1:130
	v_cvt_pk_bf16_f32 v2, v26, v27
	v_cvt_pk_bf16_f32 v3, v28, v29
	v_cvt_pk_bf16_f32 v4, v30, v31
	v_cvt_pk_bf16_f32 v5, v32, v33
	ds_write2_b64 v172, v[2:3], v[4:5] offset0:132 offset1:134
	ds_read_b64_tr_b16 v[2:3], v184
	ds_read_b64_tr_b16 v[4:5], v185 offset:1024
	ds_read_b128 v[6:9], v147 offset:4608
	ds_read_b128 v[34:37], v147 offset:4640
	s_waitcnt lgkmcnt(1)
	v_mfma_f32_32x32x16_bf16 v[2:17], v[2:5], v[6:9], 0
	ds_read_b64_tr_b16 v[38:39], v184 offset:4096
	ds_read_b64_tr_b16 v[40:41], v185 offset:5120
	ds_read_b64_tr_b16 v[168:169], v184 offset:8192
	ds_read_b64_tr_b16 v[170:171], v185 offset:9216
	ds_read_b128 v[178:181], v147 offset:4672
	s_waitcnt lgkmcnt(3)
	v_mfma_f32_32x32x16_bf16 v[34:49], v[38:41], v[34:37], 0
	s_waitcnt lgkmcnt(0)
	v_mfma_f32_32x32x16_bf16 v[2:17], v[168:171], v[178:181], v[2:17]
	ds_read_b64_tr_b16 v[168:169], v184 offset:12288
	ds_read_b64_tr_b16 v[170:171], v185 offset:13312
	ds_read_b128 v[178:181], v147 offset:4704
	s_waitcnt lgkmcnt(0)
	v_mfma_f32_32x32x16_bf16 v[34:49], v[168:171], v[178:181], v[34:49]
	s_nop 11
	v_pk_add_f32 v[16:17], v[16:17], v[48:49]
	v_pk_add_f32 v[14:15], v[14:15], v[46:47]
	v_pk_add_f32 v[12:13], v[12:13], v[44:45]
	v_pk_add_f32 v[10:11], v[10:11], v[42:43]
	v_pk_add_f32 v[8:9], v[8:9], v[40:41]
	v_pk_add_f32 v[6:7], v[6:7], v[38:39]
	v_pk_add_f32 v[4:5], v[4:5], v[36:37]
	v_pk_add_f32 v[2:3], v[2:3], v[34:35]
	v_pk_fma_f32 v[100:101], v[100:101], v[52:53], v[4:5] op_sel_hi:[1,0,1]
	v_pk_fma_f32 v[98:99], v[98:99], v[52:53], v[2:3] op_sel_hi:[1,0,1]
	v_pk_fma_f32 v[94:95], v[94:95], v[52:53], v[6:7] op_sel_hi:[1,0,1]
	v_pk_fma_f32 v[96:97], v[96:97], v[52:53], v[8:9] op_sel_hi:[1,0,1]
	v_pk_fma_f32 v[90:91], v[90:91], v[52:53], v[10:11] op_sel_hi:[1,0,1]
	v_pk_fma_f32 v[92:93], v[92:93], v[52:53], v[12:13] op_sel_hi:[1,0,1]
	v_pk_fma_f32 v[86:87], v[86:87], v[52:53], v[14:15] op_sel_hi:[1,0,1]
	v_pk_fma_f32 v[88:89], v[88:89], v[52:53], v[16:17] op_sel_hi:[1,0,1]
	v_add_u32_e32 v53, 0x2200, v53
	v_cvt_pk_bf16_f32 v2, v98, v99
	v_cvt_pk_bf16_f32 v3, v100, v101
	v_cvt_pk_bf16_f32 v4, v94, v95
	v_cvt_pk_bf16_f32 v5, v96, v97
	v_add_u32_e32 v6, 0xf000, v53
	ds_write2_b64 v6, v[2:3], v[4:5] offset0:128 offset1:130
	v_cvt_pk_bf16_f32 v2, v90, v91
	v_cvt_pk_bf16_f32 v3, v92, v93
	v_cvt_pk_bf16_f32 v4, v86, v87
	v_cvt_pk_bf16_f32 v5, v88, v89
	ds_write2_b64 v6, v[2:3], v[4:5] offset0:132 offset1:134
	v_or_b32_e32 v2, 4, v177
	v_bitop3_b32 v3, v177, v183, 4 bitop3:0x36
	v_lshlrev_b32_e32 v3, 4, v3
	v_bitop3_b32 v2, v183, v2, 1 bitop3:0x36
	v_lshlrev_b32_e32 v2, 4, v2
	v_add3_u32 v173, v182, v3, v148
	v_add3_u32 v148, v182, v2, v148
	ds_read_b64_tr_b16 v[2:3], v173
	ds_read_b64_tr_b16 v[4:5], v148 offset:1024
	ds_read_b128 v[6:9], v147
	ds_read_b128 v[34:37], v147 offset:32
	s_waitcnt lgkmcnt(1)
	v_mfma_f32_32x32x16_bf16 v[2:17], v[2:5], v[6:9], 0
	ds_read_b64_tr_b16 v[38:39], v173 offset:4096
	ds_read_b64_tr_b16 v[40:41], v148 offset:5120
	ds_read_b64_tr_b16 v[168:169], v173 offset:8192
	ds_read_b64_tr_b16 v[170:171], v148 offset:9216
	ds_read_b128 v[178:181], v147 offset:64
	s_waitcnt lgkmcnt(3)
	v_mfma_f32_32x32x16_bf16 v[34:49], v[38:41], v[34:37], 0
	s_waitcnt lgkmcnt(0)
	v_mfma_f32_32x32x16_bf16 v[2:17], v[168:171], v[178:181], v[2:17]
	ds_read_b64_tr_b16 v[168:169], v173 offset:12288
	ds_read_b64_tr_b16 v[170:171], v148 offset:13312
	ds_read_b128 v[178:181], v147 offset:96
	s_waitcnt lgkmcnt(0)
	v_mfma_f32_32x32x16_bf16 v[34:49], v[168:171], v[178:181], v[34:49]
	s_nop 11
	v_pk_add_f32 v[8:9], v[8:9], v[40:41]
	v_pk_add_f32 v[6:7], v[6:7], v[38:39]
	v_pk_add_f32 v[4:5], v[4:5], v[36:37]
	v_pk_add_f32 v[2:3], v[2:3], v[34:35]
	v_pk_add_f32 v[16:17], v[16:17], v[48:49]
	v_pk_add_f32 v[14:15], v[14:15], v[46:47]
	v_pk_add_f32 v[12:13], v[12:13], v[44:45]
	v_pk_add_f32 v[10:11], v[10:11], v[42:43]
	v_pk_fma_f32 v[82:83], v[82:83], v[52:53], v[2:3] op_sel_hi:[1,0,1]
	v_pk_fma_f32 v[84:85], v[84:85], v[52:53], v[4:5] op_sel_hi:[1,0,1]
	v_pk_fma_f32 v[78:79], v[78:79], v[52:53], v[6:7] op_sel_hi:[1,0,1]
	v_pk_fma_f32 v[80:81], v[80:81], v[52:53], v[8:9] op_sel_hi:[1,0,1]
	v_pk_fma_f32 v[74:75], v[74:75], v[52:53], v[10:11] op_sel_hi:[1,0,1]
	v_pk_fma_f32 v[76:77], v[76:77], v[52:53], v[12:13] op_sel_hi:[1,0,1]
	v_pk_fma_f32 v[70:71], v[70:71], v[52:53], v[14:15] op_sel_hi:[1,0,1]
	v_pk_fma_f32 v[72:73], v[72:73], v[52:53], v[16:17] op_sel_hi:[1,0,1]
	v_cvt_pk_bf16_f32 v2, v82, v83
	v_cvt_pk_bf16_f32 v3, v84, v85
	v_cvt_pk_bf16_f32 v4, v78, v79
	v_cvt_pk_bf16_f32 v5, v80, v81
	ds_write2_b64 v172, v[2:3], v[4:5] offset0:136 offset1:138
	v_cvt_pk_bf16_f32 v2, v74, v75
	v_cvt_pk_bf16_f32 v3, v76, v77
	v_cvt_pk_bf16_f32 v4, v70, v71
	v_cvt_pk_bf16_f32 v5, v72, v73
	ds_write2_b64 v172, v[2:3], v[4:5] offset0:140 offset1:142
	ds_read_b64_tr_b16 v[2:3], v173
	ds_read_b64_tr_b16 v[4:5], v148 offset:1024
	ds_read_b128 v[6:9], v147 offset:4608
	ds_read_b128 v[34:37], v147 offset:4640
	s_waitcnt lgkmcnt(1)
	v_mfma_f32_32x32x16_bf16 v[2:17], v[2:5], v[6:9], 0
	ds_read_b64_tr_b16 v[38:39], v173 offset:4096
	ds_read_b64_tr_b16 v[40:41], v148 offset:5120
	ds_read_b64_tr_b16 v[168:169], v173 offset:8192
	ds_read_b64_tr_b16 v[170:171], v148 offset:9216
	ds_read_b128 v[178:181], v147 offset:4672
	s_waitcnt lgkmcnt(3)
	v_mfma_f32_32x32x16_bf16 v[34:49], v[38:41], v[34:37], 0
	s_waitcnt lgkmcnt(0)
	v_mfma_f32_32x32x16_bf16 v[2:17], v[168:171], v[178:181], v[2:17]
	ds_read_b64_tr_b16 v[168:169], v173 offset:12288
	ds_read_b64_tr_b16 v[170:171], v148 offset:13312
	ds_read_b128 v[178:181], v147 offset:4704
	s_waitcnt lgkmcnt(0)
	v_mfma_f32_32x32x16_bf16 v[34:49], v[168:171], v[178:181], v[34:49]
	s_nop 11
	v_pk_add_f32 v[16:17], v[16:17], v[48:49]
	v_pk_add_f32 v[14:15], v[14:15], v[46:47]
	v_pk_add_f32 v[12:13], v[12:13], v[44:45]
	v_pk_add_f32 v[10:11], v[10:11], v[42:43]
	v_pk_add_f32 v[8:9], v[8:9], v[40:41]
	v_pk_add_f32 v[6:7], v[6:7], v[38:39]
	v_pk_add_f32 v[4:5], v[4:5], v[36:37]
	v_pk_add_f32 v[2:3], v[2:3], v[34:35]
	v_pk_fma_f32 v[68:69], v[68:69], v[52:53], v[4:5] op_sel_hi:[1,0,1]
	v_pk_fma_f32 v[66:67], v[66:67], v[52:53], v[2:3] op_sel_hi:[1,0,1]
	v_pk_fma_f32 v[62:63], v[62:63], v[52:53], v[6:7] op_sel_hi:[1,0,1]
	v_pk_fma_f32 v[64:65], v[64:65], v[52:53], v[8:9] op_sel_hi:[1,0,1]
	v_pk_fma_f32 v[58:59], v[58:59], v[52:53], v[10:11] op_sel_hi:[1,0,1]
	v_pk_fma_f32 v[60:61], v[60:61], v[52:53], v[12:13] op_sel_hi:[1,0,1]
	v_pk_fma_f32 v[54:55], v[54:55], v[52:53], v[14:15] op_sel_hi:[1,0,1]
	v_pk_fma_f32 v[56:57], v[56:57], v[52:53], v[16:17] op_sel_hi:[1,0,1]
	v_add_u32_e32 v46, 0xf440, v53
	v_cvt_pk_bf16_f32 v2, v66, v67
	v_cvt_pk_bf16_f32 v3, v68, v69
	v_mov_b64_e32 v[44:45], v[62:63]
	v_mov_b64_e32 v[42:43], v[64:65]
	v_mov_b64_e32 v[40:41], v[58:59]
	v_mov_b64_e32 v[38:39], v[60:61]
	v_mov_b64_e32 v[36:37], v[54:55]
	v_mov_b64_e32 v[34:35], v[56:57]
	ds_write_b64 v53, v[2:3] offset:62528

.LBB0_737:
	s_nop 0
.LBB0_738:
	s_waitcnt lgkmcnt(0)
	s_barrier
	s_waitcnt lgkmcnt(0)
	s_barrier
	v_add_u32_e32 v34, s82, v146
	v_cmp_gt_i32_e64 s[70:71], s59, v34
	s_and_saveexec_b64 s[82:83], s[70:71]
	s_cbranch_execz .LBB0_742
	ds_read_b128 v[34:37], v216
	ds_read_b128 v[38:41], v217
	ds_read_b128 v[42:45], v217 offset:16
	v_cmp_lt_i32_e32 vcc, 31, v146
	s_waitcnt lgkmcnt(1)
	v_pk_add_f32 v[36:37], v[36:37], v[40:41]
	v_pk_add_f32 v[40:41], v[34:35], v[38:39]
	ds_read_b128 v[46:49], v218
	s_waitcnt lgkmcnt(0)
	v_pk_add_f32 v[34:35], v[48:49], v[44:45]
	v_pk_add_f32 v[38:39], v[46:47], v[42:43]
	s_and_saveexec_b64 s[34:35], vcc
	s_cbranch_execz .LBB0_741
	ds_read_b128 v[42:45], v219
	s_waitcnt lgkmcnt(0)
	v_lshlrev_b32_e32 v46, 16, v42
	v_and_b32_e32 v47, 0xffff0000, v42
	v_lshlrev_b32_e32 v42, 16, v43
	v_and_b32_e32 v43, 0xffff0000, v43
	v_pk_add_f32 v[36:37], v[36:37], v[42:43]
	v_lshlrev_b32_e32 v42, 16, v44
	v_and_b32_e32 v43, 0xffff0000, v44
	v_lshlrev_b32_e32 v44, 16, v45
	v_and_b32_e32 v45, 0xffff0000, v45
	v_pk_add_f32 v[40:41], v[40:41], v[46:47]
	v_pk_add_f32 v[34:35], v[34:35], v[44:45]
	v_pk_add_f32 v[38:39], v[38:39], v[42:43]
